# H2 chunk totals via one ds_bpermute instead of two v_readlane + v_cndmask per value, on v18
# speedup vs baseline: 1.0028x; 1.0028x over previous
.LBB0_378:
	v_writelane_b32 v246, s52, 48
	s_cmp_lt_i32 s78, 4
	s_cselect_b64 s[2:3], -1, 0
	v_writelane_b32 v246, s53, 49
	s_add_u32 s72, s76, 0xc000000
	s_addc_u32 s73, s77, 0
	s_and_b64 s[2:3], s[2:3], s[0:1]
	v_writelane_b32 v246, s74, 50
	s_andn2_b64 vcc, exec, s[2:3]
	v_writelane_b32 v246, s88, 51
	s_nop 1
	v_writelane_b32 v246, s89, 52
	s_cbranch_vccnz .LBB0_397
	s_cmpk_gt_i32 s54, 0xff
	s_cbranch_scc1 .LBB0_397
	v_lshrrev_b32_e32 v6, 4, v170
	s_lshr_b32 s5, s48, 7
	v_and_b32_e32 v5, 15, v171
	v_lshlrev_b32_e32 v2, 2, v6
	s_lshl_b32 s8, s5, 4
	v_or_b32_e32 v9, s8, v2
	v_or_b32_e32 v150, s8, v5
	s_movk_i32 s8, 0x110
	s_bfe_u32 s6, s48, 0x10006
	v_mul_lo_u32 v10, v150, s8
	s_andn2_b32 s48, s48, 63
	s_add_i32 s8, 0, 0x1c400
	s_lshl_b32 s20, s55, 4
	s_lshl_b32 s0, s55, 5
	s_add_i32 s4, 0, 0x13c00
	v_and_b32_e32 v11, 48, v171
	s_add_i32 s9, s8, s48
	v_and_b32_e32 v16, 48, v170
	v_writelane_b32 v246, s2, 53
	v_lshrrev_b32_e32 v3, 2, v171
	s_add_i32 s0, s4, s0
	s_lshl_b32 s7, s6, 1
	s_lshl_b32 s21, s6, 6
	v_add_u32_e32 v14, s4, v11
	s_movk_i32 s4, 0x90
	s_add_i32 s12, 0, 0x11800
	v_add_u32_e32 v151, s9, v16
	v_or_b32_e32 v16, s20, v5
	v_lshl_or_b32 v24, s6, 5, v5
	v_writelane_b32 v246, s3, 54
	v_and_or_b32 v148, v3, 8, s20
	v_and_b32_e32 v4, 31, v171
	v_and_b32_e32 v7, 0xf8, v3
	v_lshlrev_b32_e32 v0, 4, v170
	v_mov_b32_e32 v1, 0
	v_or_b32_e32 v13, s21, v5
	v_mul_lo_u32 v15, v150, s4
	v_mul_lo_u32 v16, v16, s4
	v_or_b32_e32 v18, 48, v170
	v_or_b32_e32 v20, 0x70, v170
	v_or_b32_e32 v3, 7, v3
	s_cmp_le_u32 s7, s5
	v_or_b32_e32 v27, 1, v9
	v_or_b32_e32 v28, 2, v9
	v_or_b32_e32 v29, 3, v9
	v_or_b32_e32 v30, 16, v24
	v_mov_b32_e32 v33, 0x900
	v_writelane_b32 v246, s92, 55
	v_lshlrev_b32_e32 v149, 1, v4
	v_lshl_add_u64 v[78:79], s[38:39], 0, v[0:1]
	v_lshl_add_u32 v0, v6, 3, s0
	v_cmp_eq_u32_e64 s[0:1], 0, v4
	v_lshl_add_u32 v6, v148, 1, 0
	v_lshl_add_u32 v8, v4, 2, 0
	v_add_u32_e32 v10, 0, v10
	v_add_u32_e32 v12, 0, v11
	v_add_u32_e32 v15, s12, v15
	v_add_u32_e32 v16, 0, v16
	v_lshl_add_u32 v152, v148, 2, s8
	v_mul_u32_u24_e32 v17, 0x110, v5
	v_mul_u32_u24_e32 v19, 0x110, v18
	v_mul_u32_u24_e32 v21, 0x110, v20
	v_mul_u32_u24_e32 v4, 0x220, v4
	v_mul_lo_u32 v22, v148, s4
	v_mul_u32_u24_e32 v23, 0x90, v7
	v_mul_u32_u24_e32 v3, 0x90, v3
	s_cselect_b64 s[80:81], -1, 0
	v_mul_u32_u24_e32 v25, 0x110, v24
	v_mul_lo_u32 v26, v9, s4
	s_cmp_lt_u32 s7, s5
	v_mul_u32_u24_e32 v31, 0x110, v13
	v_mul_u32_u24_e32 v13, 0x90, v13
	v_mul_u32_u24_e32 v32, 0x90, v5
	v_mad_u32_u24 v5, v5, s4, v33
	v_mul_u32_u24_e32 v18, 0x90, v18
	v_mul_u32_u24_e32 v20, 0x90, v20
	v_or_b32_e32 v153, 0xc00, v7
	v_lshl_add_u32 v7, v24, 1, s12
	v_cmp_gt_u32_e64 s[4:5], v24, v9
	v_cmp_gt_u32_e64 s[6:7], v24, v27
	v_cmp_gt_u32_e64 s[8:9], v24, v28
	v_cmp_gt_u32_e64 s[10:11], v24, v29
	v_lshl_add_u32 v24, v30, 1, s12
	v_writelane_b32 v246, s93, 56
	s_mov_b32 s70, s86
	s_mov_b32 s58, s84
	s_mov_b32 s75, 0
	s_mov_b32 s59, s55
	v_cmp_gt_u32_e64 s[2:3], 32, v170
	s_cselect_b64 s[82:83], -1, 0
	v_cmp_gt_u32_e64 s[12:13], v30, v9
	v_cmp_gt_u32_e64 s[14:15], v30, v27
	v_cmp_gt_u32_e64 s[16:17], v30, v28
	v_cmp_gt_u32_e64 s[18:19], v30, v29
	v_or_b32_e32 v154, s20, v2
	v_xor_b32_e32 v155, 0xfbe, v149
	s_lshl_b32 s93, s21, 1
	v_lshlrev_b32_e32 v80, 1, v2
	s_mov_b32 s92, 0xffff0000
	s_mov_b32 s60, 0xbfb8aa3b
	v_add_u32_e32 v156, v6, v4
	v_add_u32_e32 v157, v8, v22
	v_add_u32_e32 v158, v8, v23
	v_add_u32_e32 v159, v8, v3
	v_add_u32_e32 v160, v7, v26
	v_add_u32_e32 v161, v24, v26
	v_add_u32_e32 v162, v14, v31
	v_add_u32_e32 v163, v15, v11
	v_add_u32_e32 v164, v12, v13
	v_add_u32_e32 v165, v16, v11
	v_add_u32_e32 v166, v12, v32
	v_add_u32_e32 v167, v12, v18
	v_add_u32_e32 v168, v12, v5
	v_add_u32_e32 v169, v12, v20
	v_add_u32_e32 v172, v0, v17
	v_add_u32_e32 v173, v0, v19
	v_add_u32_e32 v174, v0, v21
	v_mov_b32_e32 v175, 0xffe
	v_add_u32_e32 v176, v10, v11
	v_add_u32_e32 v177, v12, v25
	s_mov_b32 s61, s54
	s_mov_b32 s33, s54
	v_or_b32_e32 v200, 31, v170
	v_lshlrev_b32_e32 v200, 2, v200
	s_branch .LBB0_382

.LBB0_388:
	s_waitcnt vmcnt(0)
	v_lshlrev_b32_e32 v81, 16, v34
	v_and_b32_e32 v106, 0xffff0000, v34
	v_mul_f32_e64 v74, |v81|, s60
	v_lshlrev_b32_e32 v107, 16, v38
	v_and_b32_e32 v114, 0xffff0000, v38
	v_exp_f32_e32 v76, v74
	v_mul_f32_e64 v74, |v106|, s60
	v_mul_f32_e64 v104, |v107|, s60
	v_mul_f32_e64 v105, |v114|, s60
	v_exp_f32_e32 v77, v74
	v_exp_f32_e32 v104, v104
	v_exp_f32_e32 v105, v105
	v_add_f32_e32 v74, 1.0, v76
	v_add_f32_e32 v75, 1.0, v77
	v_add_f32_e32 v108, 1.0, v104
	v_add_f32_e32 v109, 1.0, v105
	v_rcp_f32_e32 v74, v74
	v_rcp_f32_e32 v75, v75
	v_rcp_f32_e32 v108, v108
	v_rcp_f32_e32 v109, v109
	v_cmp_le_f32_e32 vcc, 0, v106
	v_pk_mul_f32 v[110:111], v[76:77], v[74:75]
	v_cmp_le_f32_e64 s[22:23], 0, v81
	v_pk_mul_f32 v[112:113], v[104:105], v[108:109]
	v_cmp_le_f32_e64 s[24:25], 0, v114
	v_cmp_le_f32_e64 s[26:27], 0, v107
	v_cndmask_b32_e32 v77, v111, v75, vcc
	v_cndmask_b32_e64 v76, v110, v74, s[22:23]
	v_cndmask_b32_e64 v105, v113, v109, s[24:25]
	v_cndmask_b32_e64 v104, v112, v108, s[26:27]
	v_pk_fma_f32 v[76:77], v[94:95], v[76:77], v[82:83]
	v_pk_fma_f32 v[104:105], v[94:95], v[104:105], v[82:83]
	v_pk_mul_f32 v[104:105], v[76:77], v[104:105]
	v_lshlrev_b32_e32 v118, 16, v35
	s_nop 0
	v_mul_f32_dpp v104, v104, v104 row_shr:1 row_mask:0xf bank_mask:0xf
	v_mul_f32_dpp v105, v105, v105 row_shr:1 row_mask:0xf bank_mask:0xf
	v_and_b32_e32 v119, 0xffff0000, v35
	v_mul_f32_dpp v104, v104, v104 row_shr:2 row_mask:0xf bank_mask:0xf
	v_mul_f32_dpp v105, v105, v105 row_shr:2 row_mask:0xf bank_mask:0xf
	v_lshlrev_b32_e32 v126, 16, v39
	v_mul_f32_dpp v104, v104, v104 row_shr:4 row_mask:0xf bank_mask:0xf
	v_mul_f32_dpp v105, v105, v105 row_shr:4 row_mask:0xf bank_mask:0xf
	v_and_b32_e32 v127, 0xffff0000, v39
	v_mul_f32_dpp v104, v104, v104 row_shr:8 row_mask:0xf bank_mask:0xf
	v_mul_f32_dpp v105, v105, v105 row_shr:8 row_mask:0xf bank_mask:0xf
	v_mul_f32_e64 v116, |v126|, s60
	v_mul_f32_dpp v104, v104, v104 row_bcast:15 row_mask:0xa bank_mask:0xf
	v_mul_f32_dpp v105, v105, v105 row_bcast:15 row_mask:0xa bank_mask:0xf
	v_mul_f32_e64 v106, |v118|, s60
	v_mul_f32_e64 v107, |v119|, s60
	v_exp_f32_e32 v106, v106
	v_exp_f32_e32 v107, v107
	v_mul_f32_e64 v117, |v127|, s60
	v_exp_f32_e32 v116, v116
	v_exp_f32_e32 v117, v117
	v_add_f32_e32 v114, 1.0, v106
	v_add_f32_e32 v115, 1.0, v107
	v_rcp_f32_e32 v114, v114
	v_rcp_f32_e32 v115, v115
	v_add_f32_e32 v120, 1.0, v116
	v_add_f32_e32 v121, 1.0, v117
	v_rcp_f32_e32 v120, v120
	v_rcp_f32_e32 v121, v121
	v_pk_mul_f32 v[122:123], v[106:107], v[114:115]
	v_cmp_le_f32_e64 s[28:29], 0, v119
	v_cmp_le_f32_e64 s[30:31], 0, v118
	v_pk_mul_f32 v[124:125], v[116:117], v[120:121]
	v_cndmask_b32_e64 v107, v123, v115, s[28:29]
	v_cndmask_b32_e64 v106, v122, v114, s[30:31]
	v_cmp_le_f32_e64 s[34:35], 0, v127
	v_cmp_le_f32_e64 s[36:37], 0, v126
	v_pk_fma_f32 v[118:119], v[96:97], v[106:107], v[84:85]
	v_cndmask_b32_e64 v107, v125, v121, s[34:35]
	v_cndmask_b32_e64 v106, v124, v120, s[36:37]
	v_pk_fma_f32 v[106:107], v[96:97], v[106:107], v[84:85]
	v_pk_mul_f32 v[106:107], v[118:119], v[106:107]
	v_lshlrev_b32_e32 v130, 16, v36
	s_nop 0
	v_mul_f32_dpp v106, v106, v106 row_shr:1 row_mask:0xf bank_mask:0xf
	v_mul_f32_dpp v107, v107, v107 row_shr:1 row_mask:0xf bank_mask:0xf
	v_and_b32_e32 v131, 0xffff0000, v36
	v_mul_f32_dpp v106, v106, v106 row_shr:2 row_mask:0xf bank_mask:0xf
	v_mul_f32_dpp v107, v107, v107 row_shr:2 row_mask:0xf bank_mask:0xf
	v_lshlrev_b32_e32 v138, 16, v40
	v_mul_f32_dpp v106, v106, v106 row_shr:4 row_mask:0xf bank_mask:0xf
	v_mul_f32_dpp v107, v107, v107 row_shr:4 row_mask:0xf bank_mask:0xf
	v_and_b32_e32 v139, 0xffff0000, v40
	v_mul_f32_dpp v106, v106, v106 row_shr:8 row_mask:0xf bank_mask:0xf
	v_mul_f32_dpp v107, v107, v107 row_shr:8 row_mask:0xf bank_mask:0xf
	v_mul_f32_e64 v128, |v138|, s60
	v_mul_f32_dpp v106, v106, v106 row_bcast:15 row_mask:0xa bank_mask:0xf
	v_mul_f32_dpp v107, v107, v107 row_bcast:15 row_mask:0xa bank_mask:0xf
	v_mul_f32_e64 v116, |v130|, s60
	v_mul_f32_e64 v117, |v131|, s60
	v_exp_f32_e32 v116, v116
	v_exp_f32_e32 v117, v117
	v_mul_f32_e64 v129, |v139|, s60
	v_exp_f32_e32 v128, v128
	v_exp_f32_e32 v129, v129
	v_add_f32_e32 v126, 1.0, v116
	v_add_f32_e32 v127, 1.0, v117
	v_rcp_f32_e32 v126, v126
	v_rcp_f32_e32 v127, v127
	v_add_f32_e32 v132, 1.0, v128
	v_add_f32_e32 v133, 1.0, v129
	v_rcp_f32_e32 v132, v132
	v_rcp_f32_e32 v133, v133
	v_pk_mul_f32 v[134:135], v[116:117], v[126:127]
	v_cmp_le_f32_e64 s[38:39], 0, v131
	v_cmp_le_f32_e64 s[40:41], 0, v130
	v_pk_mul_f32 v[136:137], v[128:129], v[132:133]
	v_cndmask_b32_e64 v117, v135, v127, s[38:39]
	v_cndmask_b32_e64 v116, v134, v126, s[40:41]
	v_cmp_le_f32_e64 s[42:43], 0, v139
	v_cmp_le_f32_e64 s[44:45], 0, v138
	v_pk_fma_f32 v[128:129], v[98:99], v[116:117], v[86:87]
	v_cndmask_b32_e64 v117, v137, v133, s[42:43]
	v_cndmask_b32_e64 v116, v136, v132, s[44:45]
	v_pk_fma_f32 v[116:117], v[98:99], v[116:117], v[86:87]
	v_pk_mul_f32 v[116:117], v[128:129], v[116:117]
	v_lshlrev_b32_e32 v187, 16, v37
	s_nop 0
	v_mul_f32_dpp v116, v116, v116 row_shr:1 row_mask:0xf bank_mask:0xf
	v_mul_f32_dpp v117, v117, v117 row_shr:1 row_mask:0xf bank_mask:0xf
	v_and_b32_e32 v188, 0xffff0000, v37
	v_mul_f32_dpp v116, v116, v116 row_shr:2 row_mask:0xf bank_mask:0xf
	v_mul_f32_dpp v117, v117, v117 row_shr:2 row_mask:0xf bank_mask:0xf
	v_lshlrev_b32_e32 v189, 16, v41
	v_mul_f32_dpp v116, v116, v116 row_shr:4 row_mask:0xf bank_mask:0xf
	v_mul_f32_dpp v117, v117, v117 row_shr:4 row_mask:0xf bank_mask:0xf
	v_and_b32_e32 v190, 0xffff0000, v41
	v_mul_f32_dpp v116, v116, v116 row_shr:8 row_mask:0xf bank_mask:0xf
	v_mul_f32_dpp v117, v117, v117 row_shr:8 row_mask:0xf bank_mask:0xf
	v_mul_f32_e64 v140, |v189|, s60
	v_mul_f32_dpp v116, v116, v116 row_bcast:15 row_mask:0xa bank_mask:0xf
	v_mul_f32_dpp v117, v117, v117 row_bcast:15 row_mask:0xa bank_mask:0xf
	v_mul_f32_e64 v130, |v187|, s60
	v_mul_f32_e64 v131, |v188|, s60
	v_exp_f32_e32 v130, v130
	v_exp_f32_e32 v131, v131
	v_mul_f32_e64 v141, |v190|, s60
	v_exp_f32_e32 v140, v140
	v_exp_f32_e32 v141, v141
	v_add_f32_e32 v138, 1.0, v130
	v_add_f32_e32 v139, 1.0, v131
	v_rcp_f32_e32 v138, v138
	v_rcp_f32_e32 v139, v139
	v_add_f32_e32 v142, 1.0, v140
	v_add_f32_e32 v143, 1.0, v141
	v_rcp_f32_e32 v142, v142
	v_rcp_f32_e32 v143, v143
	v_pk_mul_f32 v[144:145], v[130:131], v[138:139]
	v_cmp_le_f32_e64 s[46:47], 0, v188
	v_cmp_le_f32_e64 s[48:49], 0, v187
	v_pk_mul_f32 v[146:147], v[140:141], v[142:143]
	v_cndmask_b32_e64 v131, v145, v139, s[46:47]
	v_cndmask_b32_e64 v130, v144, v138, s[48:49]
	v_cmp_le_f32_e64 s[50:51], 0, v190
	v_cmp_le_f32_e64 s[52:53], 0, v189
	v_pk_fma_f32 v[140:141], v[100:101], v[130:131], v[88:89]
	v_cndmask_b32_e64 v131, v147, v143, s[50:51]
	v_cndmask_b32_e64 v130, v146, v142, s[52:53]
	v_pk_fma_f32 v[130:131], v[100:101], v[130:131], v[88:89]
	v_pk_mul_f32 v[130:131], v[140:141], v[130:131]
	v_mov_b32_e32 v81, 1.0
	s_nop 0
	v_mul_f32_dpp v130, v130, v130 row_shr:1 row_mask:0xf bank_mask:0xf
	v_mul_f32_dpp v131, v131, v131 row_shr:1 row_mask:0xf bank_mask:0xf
	v_mov_b32_e32 v182, 1.0
	v_mul_f32_dpp v130, v130, v130 row_shr:2 row_mask:0xf bank_mask:0xf
	v_mul_f32_dpp v131, v131, v131 row_shr:2 row_mask:0xf bank_mask:0xf
	v_mov_b32_e32 v183, 1.0
	v_mul_f32_dpp v130, v130, v130 row_shr:4 row_mask:0xf bank_mask:0xf
	v_mul_f32_dpp v131, v131, v131 row_shr:4 row_mask:0xf bank_mask:0xf
	v_mov_b32_e32 v184, 1.0
	v_mul_f32_dpp v130, v130, v130 row_shr:8 row_mask:0xf bank_mask:0xf
	v_mul_f32_dpp v131, v131, v131 row_shr:8 row_mask:0xf bank_mask:0xf
	v_mov_b32_e32 v188, 1.0
	v_mov_b32_e32 v189, 1.0
	v_mov_b32_e32 v185, 1.0
	v_mov_b32_dpp v188, v130 row_bcast:15 row_mask:0xa bank_mask:0xf
	v_mov_b32_dpp v189, v131 row_bcast:15 row_mask:0xa bank_mask:0xf
	v_mov_b32_e32 v186, 1.0
	v_pk_mul_f32 v[130:131], v[130:131], v[188:189]
	v_mov_b32_e32 v187, 1.0
	v_mov_b32_e32 v188, 1.0
	v_mov_b32_dpp v81, v104 wave_shr:1 row_mask:0xf bank_mask:0xf
	ds_bpermute_b32 v201, v200, v104
	v_mov_b32_dpp v182, v105 wave_shr:1 row_mask:0xf bank_mask:0xf
	ds_bpermute_b32 v202, v200, v105
	v_mov_b32_dpp v183, v106 wave_shr:1 row_mask:0xf bank_mask:0xf
	ds_bpermute_b32 v203, v200, v106
	v_mov_b32_dpp v184, v107 wave_shr:1 row_mask:0xf bank_mask:0xf
	ds_bpermute_b32 v204, v200, v107
	v_mov_b32_dpp v185, v116 wave_shr:1 row_mask:0xf bank_mask:0xf
	ds_bpermute_b32 v205, v200, v116
	v_mov_b32_dpp v186, v117 wave_shr:1 row_mask:0xf bank_mask:0xf
	ds_bpermute_b32 v206, v200, v117
	v_mov_b32_dpp v187, v130 wave_shr:1 row_mask:0xf bank_mask:0xf
	ds_bpermute_b32 v207, v200, v130
	v_mov_b32_dpp v188, v131 wave_shr:1 row_mask:0xf bank_mask:0xf
	ds_bpermute_b32 v208, v200, v131
	s_cmpk_eq_i32 s55, 0x3c0
	s_cbranch_scc1 .LBB0_390
	v_add_u32_e32 v40, s55, v179
	v_add_u32_e32 v34, 64, v40
	v_add_u32_e32 v35, 1, v180
	v_add_u32_e32 v40, 0x41, v40
	v_cndmask_b32_e64 v34, v35, v34, s[20:21]
	v_cndmask_b32_e64 v40, v180, v40, s[20:21]
	v_ashrrev_i32_e32 v35, 31, v34
	v_ashrrev_i32_e32 v41, 31, v40
	v_lshlrev_b64 v[38:39], 13, v[34:35]
	v_lshlrev_b64 v[40:41], 13, v[40:41]
	v_lshl_add_u64 v[34:35], s[88:89], 0, v[38:39]
	v_lshl_add_u64 v[54:55], s[88:89], 0, v[40:41]
	v_lshl_add_u64 v[36:37], v[34:35], 0, v[0:1]
	v_lshl_add_u64 v[34:35], v[34:35], 0, v[92:93]
	v_lshl_add_u64 v[38:39], v[90:91], 0, v[38:39]
	v_lshl_add_u64 v[50:51], v[54:55], 0, v[0:1]
	global_load_dwordx4 v[42:45], v[36:37], off
	s_nop 0
	global_load_dwordx4 v[34:37], v[34:35], off offset:2048
	s_nop 0
	global_load_dwordx4 v[46:49], v[38:39], off
	s_nop 0
	global_load_dwordx4 v[50:53], v[50:51], off
	v_lshl_add_u64 v[38:39], v[54:55], 0, v[92:93]
	v_lshl_add_u64 v[54:55], v[90:91], 0, v[40:41]
	global_load_dwordx4 v[38:41], v[38:39], off offset:2048
	s_nop 0
	global_load_dwordx4 v[54:57], v[54:55], off
.LBB0_390:
	v_cndmask_b32_e32 v75, v75, v111, vcc
	v_cndmask_b32_e64 v74, v74, v110, s[22:23]
	v_pk_mul_f32 v[190:191], v[94:95], v[74:75]
	v_cndmask_b32_e64 v75, v109, v113, s[24:25]
	v_cndmask_b32_e64 v74, v108, v112, s[26:27]
	v_lshlrev_b32_e32 v112, 16, v66
	v_and_b32_e32 v113, 0xffff0000, v66
	v_lshlrev_b32_e32 v194, 16, v70
	v_and_b32_e32 v195, 0xffff0000, v70
	v_cndmask_b32_e64 v108, v81, 1.0, s[0:1]
	v_cndmask_b32_e64 v109, v182, 1.0, s[0:1]
	v_pk_mul_f32 v[192:193], v[94:95], v[74:75]
	s_waitcnt lgkmcnt(0)
	v_mov_b32_e32 v74, v201
	v_pk_mul_f32 v[196:197], v[76:77], v[108:109]
	v_cndmask_b32_e64 v77, v115, v123, s[28:29]
	v_cndmask_b32_e64 v76, v114, v122, s[30:31]
	v_mov_b32_e32 v70, v202
	v_pk_mul_f32 v[114:115], v[96:97], v[76:77]
	v_cndmask_b32_e64 v77, v121, v125, s[34:35]
	v_cndmask_b32_e64 v76, v120, v124, s[36:37]
	v_lshlrev_b32_e32 v120, 16, v67
	v_and_b32_e32 v121, 0xffff0000, v67
	v_cndmask_b32_e64 v66, v183, 1.0, s[0:1]
	v_cndmask_b32_e64 v67, v184, 1.0, s[0:1]
	v_pk_mul_f32 v[118:119], v[118:119], v[66:67]
	v_cndmask_b32_e64 v110, v185, 1.0, s[0:1]
	v_cndmask_b32_e64 v111, v186, 1.0, s[0:1]
	v_rcp_f32_e32 v184, v118
	v_rcp_f32_e32 v185, v119
	v_pk_mul_f32 v[128:129], v[128:129], v[110:111]
	v_cndmask_b32_e64 v111, v139, v145, s[46:47]
	v_cndmask_b32_e64 v110, v138, v144, s[48:49]
	v_pk_mul_f32 v[138:139], v[100:101], v[110:111]
	v_cndmask_b32_e64 v111, v143, v147, s[50:51]
	v_cndmask_b32_e64 v110, v142, v146, s[52:53]
	v_pk_mul_f32 v[142:143], v[100:101], v[110:111]
	v_cndmask_b32_e64 v110, v187, 1.0, s[0:1]
	v_cndmask_b32_e64 v111, v188, 1.0, s[0:1]
	v_pk_mul_f32 v[140:141], v[140:141], v[110:111]
	v_pk_mul_f32 v[184:185], v[114:115], v[184:185]
	v_rcp_f32_e32 v114, v128
	v_rcp_f32_e32 v115, v129
	v_pk_mul_f32 v[118:119], v[118:119], v[120:121]
	v_rcp_f32_e32 v120, v140
	v_rcp_f32_e32 v121, v141
	v_mov_b32_e32 v108, v204
	v_cndmask_b32_e64 v67, v127, v135, s[38:39]
	v_cndmask_b32_e64 v66, v126, v134, s[40:41]
	v_lshlrev_b32_e32 v134, 16, v68
	v_and_b32_e32 v135, 0xffff0000, v68
	v_rcp_f32_e32 v182, v196
	v_rcp_f32_e32 v183, v197
	v_pk_mul_f32 v[126:127], v[98:99], v[66:67]
	v_pk_mul_f32 v[128:129], v[128:129], v[134:135]
	v_lshlrev_b32_e32 v144, 16, v69
	v_and_b32_e32 v145, 0xffff0000, v69
	v_pk_mul_f32 v[126:127], v[126:127], v[114:115]
	v_cvt_pk_bf16_f32 v114, v128, v129
	v_rcp_f32_e32 v128, v104
	v_rcp_f32_e32 v129, v105
	v_pk_mul_f32 v[112:113], v[196:197], v[112:113]
	v_pk_mul_f32 v[134:135], v[140:141], v[144:145]
	v_pk_mul_f32 v[138:139], v[138:139], v[120:121]
	v_lshlrev_b32_e32 v124, 16, v71
	v_and_b32_e32 v125, 0xffff0000, v71
	v_pk_mul_f32 v[182:183], v[190:191], v[182:183]
	v_cvt_pk_bf16_f32 v112, v112, v113
	v_cvt_pk_bf16_f32 v113, v118, v119
	v_cvt_pk_bf16_f32 v115, v134, v135
	v_cvt_pk_bf16_f32 v120, v126, v127
	v_cvt_pk_bf16_f32 v121, v138, v139
	v_cvt_pk_bf16_f32 v118, v182, v183
	v_cvt_pk_bf16_f32 v119, v184, v185
	ds_write_b128 v156, v[112:115]
	ds_write_b128 v156, v[118:121] offset:17408
	v_rcp_f32_e32 v120, v106
	v_rcp_f32_e32 v121, v107
	v_pk_mul_f32 v[106:107], v[106:107], v[124:125]
	v_rcp_f32_e32 v124, v116
	v_rcp_f32_e32 v125, v117
	v_rcp_f32_e32 v134, v130
	v_rcp_f32_e32 v135, v131
	v_cndmask_b32_e64 v67, v133, v137, s[42:43]
	v_cndmask_b32_e64 v66, v132, v136, s[44:45]
	v_pk_mul_f32 v[112:113], v[192:193], v[128:129]
	v_pk_mul_f32 v[132:133], v[98:99], v[66:67]
	v_mov_b32_e32 v114, v182
	v_mov_b32_e32 v115, v112
	v_pk_mul_f32 v[122:123], v[96:97], v[76:77]
	v_mov_b32_e32 v66, v205
	v_pk_mul_f32 v[118:119], v[114:115], v[74:75] op_sel_hi:[1,0]
	v_mov_b32_e32 v114, v183
	v_mov_b32_e32 v115, v113
	v_lshlrev_b32_e32 v136, 16, v72
	v_and_b32_e32 v137, 0xffff0000, v72
	v_mov_b32_e32 v72, v206
	v_lshlrev_b32_e32 v146, 16, v73
	v_and_b32_e32 v147, 0xffff0000, v73
	v_pk_mul_f32 v[128:129], v[114:115], v[70:71] op_sel_hi:[1,0]
	v_pk_mul_f32 v[114:115], v[122:123], v[120:121]
	v_pk_mul_f32 v[124:125], v[132:133], v[124:125]
	v_pk_mul_f32 v[134:135], v[142:143], v[134:135]
	v_mov_b32_e32 v76, v203
	v_mov_b32_e32 v68, v207
	v_pk_mul_f32 v[104:105], v[104:105], v[194:195]
	v_mov_b32_e32 v120, v184
	v_mov_b32_e32 v121, v114
	v_mov_b32_e32 v122, v185
	v_mov_b32_e32 v123, v115
	v_pk_mul_f32 v[116:117], v[116:117], v[136:137]
	v_mov_b32_e32 v132, v126
	v_mov_b32_e32 v133, v124
	v_pk_mul_f32 v[130:131], v[130:131], v[146:147]
	v_mov_b32_e32 v136, v138
	v_mov_b32_e32 v137, v134
	v_mov_b32_e32 v110, v208
	v_pk_mul_f32 v[120:121], v[120:121], v[76:77] op_sel_hi:[1,0]
	v_pk_mul_f32 v[122:123], v[122:123], v[108:109] op_sel_hi:[1,0]
	v_pk_mul_f32 v[132:133], v[132:133], v[66:67] op_sel_hi:[1,0]
	v_mov_b32_e32 v126, v127
	v_mov_b32_e32 v127, v125
	v_pk_mul_f32 v[136:137], v[136:137], v[68:69] op_sel_hi:[1,0]
	v_cvt_pk_bf16_f32 v104, v104, v105
	v_cvt_pk_bf16_f32 v105, v106, v107
	v_cvt_pk_bf16_f32 v106, v116, v117
	v_cvt_pk_bf16_f32 v107, v130, v131
	v_cvt_pk_bf16_f32 v67, v118, v119
	v_cvt_pk_bf16_f32 v69, v128, v129
	v_add_u32_e32 v71, 0x8800, v157
	v_pk_mul_f32 v[126:127], v[126:127], v[72:73] op_sel_hi:[1,0]
	v_mov_b32_e32 v138, v139
	v_mov_b32_e32 v139, v135
	v_cvt_pk_bf16_f32 v112, v112, v113
	v_cvt_pk_bf16_f32 v113, v114, v115
	v_cvt_pk_bf16_f32 v114, v124, v125
	v_cvt_pk_bf16_f32 v115, v134, v135
	ds_write_b128 v156, v[104:107] offset:272
	ds_write_b128 v156, v[112:115] offset:17680
	ds_write2_b32 v71, v67, v69 offset1:36
	v_cvt_pk_bf16_f32 v67, v120, v121
	v_cvt_pk_bf16_f32 v69, v122, v123
	v_pk_mul_f32 v[138:139], v[138:139], v[110:111] op_sel_hi:[1,0]
	ds_write2_b32 v71, v67, v69 offset0:72 offset1:108
	v_cvt_pk_bf16_f32 v67, v132, v133
	v_cvt_pk_bf16_f32 v69, v126, v127
	ds_write2_b32 v71, v67, v69 offset0:144 offset1:180
	v_cvt_pk_bf16_f32 v67, v136, v137
	v_cvt_pk_bf16_f32 v69, v138, v139
	ds_write2_b32 v71, v67, v69 offset0:216 offset1:252
	s_and_saveexec_b64 s[22:23], s[0:1]
	s_cbranch_execz .LBB0_392
	v_mov_b32_e32 v75, v70
	v_mov_b32_e32 v77, v108
	v_mov_b32_e32 v67, v72
	v_mov_b32_e32 v69, v110
	ds_write_b128 v152, v[74:77]
	ds_write_b128 v152, v[66:69] offset:16
